# last out-proj epilogue: 16-B residual loads (permlane16_swap regroup) requested up front; row-statistic loads hoisted, no per-row store drain
# speedup vs baseline: 1.0357x; 1.0003x over previous
; #define PG8_LAS __attribute__((address_space(3)))
;     __device__ __forceinline__ void fused(f32x4 (&acc)[2][2][4][2], const Unit& u, int wr, int wc, int fr, int fq, PG8_LAS unsigned char*, int wid, int lane) const {
;         typedef unsigned u32x2 __attribute__((ext_vector_type(2)));
;         const int col0 = u.pn * BM + wc * 32 + 4 * fq;
; #pragma unroll
;         for (int ai = 0; ai < 2; ++ai)
; #pragma unroll
;             for (int m = 0; m < 4; ++m) {
;                 const int row = u.pm * BM + ai * HALF + wr * 64 + m * 16 + fr;
;                 const size_t off = (size_t)row * 1024 + col0;
;                 float ss = 0.f;
; #pragma unroll
;                 for (int bj = 0; bj < 2; ++bj)
; #pragma unroll
;                     for (int n = 0; n < 2; ++n) { const u32x2 hb = *(const u32x2*)(baseh + off + bj * HALF + n * 16);
;                         const f32x4 o = (f32x4){__uint_as_float(hb.x << 16), __uint_as_float(hb.x & 0xffff0000u), __uint_as_float(hb.y << 16), __uint_as_float(hb.y & 0xffff0000u)} + acc[ai][bj][m][n]; acc[ai][bj][m][n] = o;
;                         ss += (o[0] * o[0] + o[1] * o[1]) + (o[2] * o[2] + o[3] * o[3]); }
;                 ss += __shfl_xor(ss, 16); ss += __shfl_xor(ss, 32);
;                 if (fq == 0) (void)__hip_atomic_fetch_add(rowss2 + row, ss, __ATOMIC_RELAXED, __HIP_MEMORY_SCOPE_AGENT);
;                 if (m & 1) asm volatile("" ::: "memory");
;             }
.LBB0_983:
	v_and_b32_e32 v134, 64, v237
	v_xor_b32_e32 v131, 16, v237
	v_add_u32_e32 v134, 64, v134
	v_cmp_lt_i32_e32 vcc, v131, v134
	v_lshrrev_b32_e32 v130, 2, v140
	v_and_b32_e32 v130, 12, v130
	v_cndmask_b32_e32 v131, v237, v131, vcc
	s_lshl_b32 s0, s10, 8
	v_lshlrev_b32_e32 v178, 2, v131
	v_xor_b32_e32 v131, 32, v237
	v_lshl_or_b32 v130, s62, 8, v130
	s_add_i32 s0, s0, s46
	v_cmp_lt_i32_e32 vcc, v131, v134
	v_or_b32_e32 v132, s52, v130
	v_or_b32_e32 v130, s0, v141
	v_cndmask_b32_e32 v131, v237, v131, vcc
	v_lshlrev_b32_e32 v179, 2, v131
	v_ashrrev_i32_e32 v131, 31, v130
	v_lshlrev_b64 v[134:135], 11, v[130:131]
	v_ashrrev_i32_e32 v133, 31, v132
	v_lshl_add_u64 v[134:135], s[94:95], 0, v[134:135]
	v_lshl_add_u64 v[134:135], v[132:133], 1, v[134:135]
	v_and_b32_e32 v222, 0xfffffff3, v132
	v_and_b32_e32 v223, 16, v237
	v_or_b32_e32 v222, v222, v223
	v_and_b32_e32 v223, 32, v237
	v_lshrrev_b32_e32 v223, 2, v223
	v_or_b32_e32 v222, v222, v223
	v_lshlrev_b32_e32 v232, 11, v130
	v_lshl_add_u32 v232, v222, 1, v232
	global_load_dwordx4 v[184:187], v232, s[94:95]
	global_load_dwordx4 v[188:191], v232, s[94:95] offset:256
	v_add_u32_e32 v233, 0x8000, v232
	global_load_dwordx4 v[192:195], v233, s[94:95]
	v_add_u32_e32 v233, 0x8000, v232
	global_load_dwordx4 v[196:199], v233, s[94:95] offset:256
	v_add_u32_e32 v233, 0x10000, v232
	global_load_dwordx4 v[200:203], v233, s[94:95]
	v_add_u32_e32 v233, 0x10000, v232
	global_load_dwordx4 v[204:207], v233, s[94:95] offset:256
	v_add_u32_e32 v233, 0x18000, v232
	global_load_dwordx4 v[208:211], v233, s[94:95]
	v_add_u32_e32 v233, 0x18000, v232
	global_load_dwordx4 v[212:215], v233, s[94:95] offset:256
	v_add_u32_e32 v233, 0x40000, v232
	global_load_dwordx4 v[216:219], v233, s[94:95]
	v_add_u32_e32 v233, 0x40000, v232
	global_load_dwordx4 v[224:227], v233, s[94:95] offset:256
	v_add_u32_e32 v233, 0x48000, v232
	global_load_dwordx4 v[228:231], v233, s[94:95]
	v_add_u32_e32 v233, 0x48000, v232
	global_load_dwordx4 v[244:247], v233, s[94:95] offset:256
	v_add_u32_e32 v233, 0x50000, v232
	global_load_dwordx4 v[248:251], v233, s[94:95]
	s_barrier
	s_waitcnt vmcnt(11)
	v_permlane16_swap_b32_e32 v184, v186
	v_permlane16_swap_b32_e32 v185, v187
	v_permlane16_swap_b32_e32 v188, v190
	v_permlane16_swap_b32_e32 v189, v191
	v_mov_b32_e32 v136, v184
	v_mov_b32_e32 v137, v185
	v_and_b32_e32 v180, 63, v140
	v_readlane_b32 s0, v253, 50
	v_readlane_b32 s1, v253, 51
	v_cmp_gt_u32_e32 vcc, 16, v180
	v_lshlrev_b32_e32 v138, 16, v136
	v_and_b32_e32 v139, 0xffff0000, v136
	v_lshlrev_b32_e32 v136, 16, v137
	v_and_b32_e32 v137, 0xffff0000, v137
	v_pk_add_f32 v[126:127], v[126:127], v[136:137]
	v_pk_add_f32 v[124:125], v[124:125], v[138:139]
	v_mul_f32_e32 v137, v127, v127
	v_mul_f32_e32 v136, v125, v125
	v_fmac_f32_e32 v136, v124, v124
	v_fmac_f32_e32 v137, v126, v126
	v_add_f32_e32 v140, v136, v137
	v_mov_b32_e32 v136, v186
	v_mov_b32_e32 v137, v187
	v_lshlrev_b32_e32 v138, 16, v136
	v_and_b32_e32 v139, 0xffff0000, v136
	v_lshlrev_b32_e32 v136, 16, v137
	v_and_b32_e32 v137, 0xffff0000, v137
	v_pk_add_f32 v[122:123], v[122:123], v[136:137]
	v_pk_add_f32 v[120:121], v[120:121], v[138:139]
	v_mul_f32_e32 v137, v123, v123
	v_mul_f32_e32 v136, v121, v121
	v_fmac_f32_e32 v136, v120, v120
	v_fmac_f32_e32 v137, v122, v122
	v_add_f32_e32 v136, v136, v137
	v_add_f32_e32 v140, v140, v136
	v_mov_b32_e32 v136, v188
	v_mov_b32_e32 v137, v189
	v_lshlrev_b32_e32 v138, 16, v136
	v_mov_b32_e32 v134, v190
	v_mov_b32_e32 v135, v191
	v_and_b32_e32 v139, 0xffff0000, v136
	v_lshlrev_b32_e32 v136, 16, v137
	v_and_b32_e32 v137, 0xffff0000, v137
	v_pk_add_f32 v[118:119], v[118:119], v[136:137]
	v_pk_add_f32 v[116:117], v[116:117], v[138:139]
	v_mul_f32_e32 v137, v119, v119
	v_mul_f32_e32 v136, v117, v117
	v_fmac_f32_e32 v136, v116, v116
	v_fmac_f32_e32 v137, v118, v118
	v_add_f32_e32 v136, v136, v137
	v_add_f32_e32 v138, v140, v136
	v_lshlrev_b32_e32 v136, 16, v134
	v_and_b32_e32 v137, 0xffff0000, v134
	v_lshlrev_b32_e32 v134, 16, v135
	v_and_b32_e32 v135, 0xffff0000, v135
	v_pk_add_f32 v[114:115], v[114:115], v[134:135]
	v_pk_add_f32 v[112:113], v[112:113], v[136:137]
	v_mul_f32_e32 v135, v115, v115
	v_mul_f32_e32 v134, v113, v113
	v_fmac_f32_e32 v134, v112, v112
	v_fmac_f32_e32 v135, v114, v114
	v_add_f32_e32 v134, v134, v135
	v_add_f32_e32 v134, v138, v134
	ds_bpermute_b32 v135, v178, v134
	v_lshl_add_u64 v[136:137], v[130:131], 2, s[0:1]
	s_waitcnt lgkmcnt(0)
	v_add_f32_e32 v134, v134, v135
	ds_bpermute_b32 v135, v179, v134
	s_and_saveexec_b64 s[0:1], vcc
	v_readlane_b32 s54, v254, 56
	v_readlane_b32 s31, v255, 0
	v_readlane_b32 s52, v254, 54
	v_readlane_b32 s53, v254, 55
	v_readlane_b32 s55, v254, 57
	v_readlane_b32 s20, v254, 62
	v_readlane_b32 s21, v254, 63
	s_cbranch_execz .LBB0_985
	s_waitcnt lgkmcnt(0)
	v_add_f32_e32 v134, v134, v135
	global_atomic_add_f32 v[136:137], v134, off
; #define PG8_LAS __attribute__((address_space(3)))
;     __device__ __forceinline__ void fused(f32x4 (&acc)[2][2][4][2], const Unit& u, int wr, int wc, int fr, int fq, PG8_LAS unsigned char*, int wid, int lane) const {
;         typedef unsigned u32x2 __attribute__((ext_vector_type(2)));
;         const int col0 = u.pn * BM + wc * 32 + 4 * fq;
; #pragma unroll
;         for (int ai = 0; ai < 2; ++ai)
; #pragma unroll
;             for (int m = 0; m < 4; ++m) {
;                 const int row = u.pm * BM + ai * HALF + wr * 64 + m * 16 + fr;
;                 const size_t off = (size_t)row * 1024 + col0;
;                 float ss = 0.f;
; #pragma unroll
;                 for (int bj = 0; bj < 2; ++bj)
; #pragma unroll
;                     for (int n = 0; n < 2; ++n) { const u32x2 hb = *(const u32x2*)(baseh + off + bj * HALF + n * 16);
;                         const f32x4 o = (f32x4){__uint_as_float(hb.x << 16), __uint_as_float(hb.x & 0xffff0000u), __uint_as_float(hb.y << 16), __uint_as_float(hb.y & 0xffff0000u)} + acc[ai][bj][m][n]; acc[ai][bj][m][n] = o;
;                         ss += (o[0] * o[0] + o[1] * o[1]) + (o[2] * o[2] + o[3] * o[3]); }
;                 ss += __shfl_xor(ss, 16); ss += __shfl_xor(ss, 32);
;                 if (fq == 0) (void)__hip_atomic_fetch_add(rowss2 + row, ss, __ATOMIC_RELAXED, __HIP_MEMORY_SCOPE_AGENT);
;                 if (m & 1) asm volatile("" ::: "memory");
;             }
.LBB0_985:
	s_or_b64 exec, exec, s[0:1]
	v_or_b32_e32 v134, 16, v130
	s_waitcnt lgkmcnt(0)
	v_ashrrev_i32_e32 v135, 31, v134
	v_lshlrev_b64 v[138:139], 11, v[134:135]
	v_lshl_add_u64 v[138:139], s[94:95], 0, v[138:139]
	v_lshl_add_u64 v[138:139], v[132:133], 1, v[138:139]
	s_waitcnt vmcnt(10)
	v_permlane16_swap_b32_e32 v192, v194
	v_permlane16_swap_b32_e32 v193, v195
	v_permlane16_swap_b32_e32 v196, v198
	v_permlane16_swap_b32_e32 v197, v199
	v_mov_b32_e32 v140, v192
	v_mov_b32_e32 v141, v193
	v_readlane_b32 s0, v253, 50
	v_readlane_b32 s1, v253, 51
	v_lshlrev_b32_e32 v142, 16, v140
	v_and_b32_e32 v143, 0xffff0000, v140
	v_lshlrev_b32_e32 v140, 16, v141
	v_and_b32_e32 v141, 0xffff0000, v141
	v_pk_add_f32 v[110:111], v[110:111], v[140:141]
	v_pk_add_f32 v[108:109], v[108:109], v[142:143]
	v_mul_f32_e32 v141, v111, v111
	v_mul_f32_e32 v140, v109, v109
	v_fmac_f32_e32 v140, v108, v108
	v_fmac_f32_e32 v141, v110, v110
	v_add_f32_e32 v144, v140, v141
	v_mov_b32_e32 v140, v194
	v_mov_b32_e32 v141, v195
	v_lshlrev_b32_e32 v142, 16, v140
	v_and_b32_e32 v143, 0xffff0000, v140
	v_lshlrev_b32_e32 v140, 16, v141
	v_and_b32_e32 v141, 0xffff0000, v141
	v_pk_add_f32 v[106:107], v[106:107], v[140:141]
	v_pk_add_f32 v[104:105], v[104:105], v[142:143]
	v_mul_f32_e32 v141, v107, v107
	v_mul_f32_e32 v140, v105, v105
	v_fmac_f32_e32 v140, v104, v104
	v_fmac_f32_e32 v141, v106, v106
	v_add_f32_e32 v140, v140, v141
	v_add_f32_e32 v144, v144, v140
	v_mov_b32_e32 v140, v196
	v_mov_b32_e32 v141, v197
	v_lshlrev_b32_e32 v142, 16, v140
	v_mov_b32_e32 v138, v198
	v_mov_b32_e32 v139, v199
	v_add_u32_e32 v233, 0x50000, v232
	global_load_dwordx4 v[184:187], v233, s[94:95] offset:256
	v_add_u32_e32 v233, 0x58000, v232
	global_load_dwordx4 v[188:191], v233, s[94:95]
	v_add_u32_e32 v233, 0x58000, v232
	global_load_dwordx4 v[192:195], v233, s[94:95] offset:256
	v_and_b32_e32 v143, 0xffff0000, v140
	v_lshlrev_b32_e32 v140, 16, v141
	v_and_b32_e32 v141, 0xffff0000, v141
	v_pk_add_f32 v[102:103], v[102:103], v[140:141]
	v_pk_add_f32 v[100:101], v[100:101], v[142:143]
	v_mul_f32_e32 v141, v103, v103
	v_mul_f32_e32 v140, v101, v101
	v_fmac_f32_e32 v140, v100, v100
	v_fmac_f32_e32 v141, v102, v102
	v_add_f32_e32 v140, v140, v141
	v_add_f32_e32 v142, v144, v140
	v_lshlrev_b32_e32 v140, 16, v138
	v_and_b32_e32 v141, 0xffff0000, v138
	v_lshlrev_b32_e32 v138, 16, v139
	v_and_b32_e32 v139, 0xffff0000, v139
	v_pk_add_f32 v[98:99], v[98:99], v[138:139]
	v_pk_add_f32 v[96:97], v[96:97], v[140:141]
	v_mul_f32_e32 v139, v99, v99
	v_mul_f32_e32 v138, v97, v97
	v_fmac_f32_e32 v138, v96, v96
	v_fmac_f32_e32 v139, v98, v98
	v_add_f32_e32 v138, v138, v139
	v_add_f32_e32 v138, v142, v138
	ds_bpermute_b32 v139, v178, v138
	v_lshl_add_u64 v[140:141], v[134:135], 2, s[0:1]
	s_waitcnt lgkmcnt(0)
	v_add_f32_e32 v138, v138, v139
	ds_bpermute_b32 v139, v179, v138
	s_and_saveexec_b64 s[0:1], vcc
	s_cbranch_execz .LBB0_987
	s_waitcnt lgkmcnt(0)
	v_add_f32_e32 v138, v138, v139
	global_atomic_add_f32 v[140:141], v138, off
.LBB0_987:
	s_or_b64 exec, exec, s[0:1]
	v_or_b32_e32 v138, 32, v130
	s_waitcnt lgkmcnt(0)
	v_ashrrev_i32_e32 v139, 31, v138
	v_lshlrev_b64 v[142:143], 11, v[138:139]
	v_lshl_add_u64 v[142:143], s[94:95], 0, v[142:143]
	v_lshl_add_u64 v[142:143], v[132:133], 1, v[142:143]
	s_waitcnt vmcnt(12)
	v_permlane16_swap_b32_e32 v200, v202
	v_permlane16_swap_b32_e32 v201, v203
	v_permlane16_swap_b32_e32 v204, v206
	v_permlane16_swap_b32_e32 v205, v207
	v_mov_b32_e32 v144, v200
	v_mov_b32_e32 v145, v201
	v_readlane_b32 s0, v253, 50
	v_readlane_b32 s1, v253, 51
	v_lshlrev_b32_e32 v146, 16, v144
	v_and_b32_e32 v147, 0xffff0000, v144
	v_lshlrev_b32_e32 v144, 16, v145
	v_and_b32_e32 v145, 0xffff0000, v145
	v_pk_add_f32 v[94:95], v[94:95], v[144:145]
	v_pk_add_f32 v[92:93], v[92:93], v[146:147]
	v_mul_f32_e32 v145, v95, v95
	v_mul_f32_e32 v144, v93, v93
	v_fmac_f32_e32 v144, v92, v92
	v_fmac_f32_e32 v145, v94, v94
	v_add_f32_e32 v148, v144, v145
	v_mov_b32_e32 v144, v202
	v_mov_b32_e32 v145, v203
	v_lshlrev_b32_e32 v146, 16, v144
	v_and_b32_e32 v147, 0xffff0000, v144
	v_lshlrev_b32_e32 v144, 16, v145
	v_and_b32_e32 v145, 0xffff0000, v145
	v_pk_add_f32 v[90:91], v[90:91], v[144:145]
	v_pk_add_f32 v[88:89], v[88:89], v[146:147]
	v_mul_f32_e32 v145, v91, v91
	v_mul_f32_e32 v144, v89, v89
	v_fmac_f32_e32 v144, v88, v88
	v_fmac_f32_e32 v145, v90, v90
	v_add_f32_e32 v144, v144, v145
	v_add_f32_e32 v148, v148, v144
	v_mov_b32_e32 v144, v204
	v_mov_b32_e32 v145, v205
	v_lshlrev_b32_e32 v146, 16, v144
	v_mov_b32_e32 v142, v206
	v_mov_b32_e32 v143, v207
	v_and_b32_e32 v147, 0xffff0000, v144
	v_lshlrev_b32_e32 v144, 16, v145
	v_and_b32_e32 v145, 0xffff0000, v145
	v_pk_add_f32 v[86:87], v[86:87], v[144:145]
	v_pk_add_f32 v[84:85], v[84:85], v[146:147]
	v_mul_f32_e32 v145, v87, v87
	v_mul_f32_e32 v144, v85, v85
	v_fmac_f32_e32 v144, v84, v84
	v_fmac_f32_e32 v145, v86, v86
	v_add_f32_e32 v144, v144, v145
	v_add_f32_e32 v146, v148, v144
	v_lshlrev_b32_e32 v144, 16, v142
	v_and_b32_e32 v145, 0xffff0000, v142
	v_lshlrev_b32_e32 v142, 16, v143
	v_and_b32_e32 v143, 0xffff0000, v143
	v_pk_add_f32 v[82:83], v[82:83], v[142:143]
	v_pk_add_f32 v[80:81], v[80:81], v[144:145]
	v_mul_f32_e32 v143, v83, v83
	v_mul_f32_e32 v142, v81, v81
	v_fmac_f32_e32 v142, v80, v80
	v_fmac_f32_e32 v143, v82, v82
	v_add_f32_e32 v142, v142, v143
	v_add_f32_e32 v142, v146, v142
	ds_bpermute_b32 v143, v178, v142
	v_lshl_add_u64 v[144:145], v[138:139], 2, s[0:1]
	s_waitcnt lgkmcnt(0)
	v_add_f32_e32 v142, v142, v143
	ds_bpermute_b32 v143, v179, v142
	s_and_saveexec_b64 s[0:1], vcc
	s_cbranch_execz .LBB0_989
	s_waitcnt lgkmcnt(0)
	v_add_f32_e32 v142, v142, v143
	global_atomic_add_f32 v[144:145], v142, off
; #define PG8_LAS __attribute__((address_space(3)))
;     __device__ __forceinline__ void fused(f32x4 (&acc)[2][2][4][2], const Unit& u, int wr, int wc, int fr, int fq, PG8_LAS unsigned char*, int wid, int lane) const {
;         typedef unsigned u32x2 __attribute__((ext_vector_type(2)));
;         const int col0 = u.pn * BM + wc * 32 + 4 * fq;
; #pragma unroll
;         for (int ai = 0; ai < 2; ++ai)
; #pragma unroll
;             for (int m = 0; m < 4; ++m) {
;                 const int row = u.pm * BM + ai * HALF + wr * 64 + m * 16 + fr;
;                 const size_t off = (size_t)row * 1024 + col0;
;                 float ss = 0.f;
; #pragma unroll
;                 for (int bj = 0; bj < 2; ++bj)
; #pragma unroll
;                     for (int n = 0; n < 2; ++n) { const u32x2 hb = *(const u32x2*)(baseh + off + bj * HALF + n * 16);
;                         const f32x4 o = (f32x4){__uint_as_float(hb.x << 16), __uint_as_float(hb.x & 0xffff0000u), __uint_as_float(hb.y << 16), __uint_as_float(hb.y & 0xffff0000u)} + acc[ai][bj][m][n]; acc[ai][bj][m][n] = o;
;                         ss += (o[0] * o[0] + o[1] * o[1]) + (o[2] * o[2] + o[3] * o[3]); }
;                 ss += __shfl_xor(ss, 16); ss += __shfl_xor(ss, 32);
;                 if (fq == 0) (void)__hip_atomic_fetch_add(rowss2 + row, ss, __ATOMIC_RELAXED, __HIP_MEMORY_SCOPE_AGENT);
;                 if (m & 1) asm volatile("" ::: "memory");
;             }
.LBB0_989:
	s_or_b64 exec, exec, s[0:1]
	v_or_b32_e32 v142, 48, v130
	s_waitcnt lgkmcnt(0)
	v_ashrrev_i32_e32 v143, 31, v142
	v_lshlrev_b64 v[146:147], 11, v[142:143]
	v_lshl_add_u64 v[146:147], s[94:95], 0, v[146:147]
	v_lshl_add_u64 v[146:147], v[132:133], 1, v[146:147]
	s_waitcnt vmcnt(11)
	v_permlane16_swap_b32_e32 v208, v210
	v_permlane16_swap_b32_e32 v209, v211
	v_permlane16_swap_b32_e32 v212, v214
	v_permlane16_swap_b32_e32 v213, v215
	v_mov_b32_e32 v148, v208
	v_mov_b32_e32 v149, v209
	v_readlane_b32 s0, v253, 50
	v_readlane_b32 s1, v253, 51
	v_lshlrev_b32_e32 v150, 16, v148
	v_and_b32_e32 v151, 0xffff0000, v148
	v_lshlrev_b32_e32 v148, 16, v149
	v_and_b32_e32 v149, 0xffff0000, v149
	v_pk_add_f32 v[78:79], v[78:79], v[148:149]
	v_pk_add_f32 v[76:77], v[76:77], v[150:151]
	v_mul_f32_e32 v149, v79, v79
	v_mul_f32_e32 v148, v77, v77
	v_fmac_f32_e32 v148, v76, v76
	v_fmac_f32_e32 v149, v78, v78
	v_add_f32_e32 v152, v148, v149
	v_mov_b32_e32 v148, v210
	v_mov_b32_e32 v149, v211
	v_lshlrev_b32_e32 v150, 16, v148
	v_and_b32_e32 v151, 0xffff0000, v148
	v_lshlrev_b32_e32 v148, 16, v149
	v_and_b32_e32 v149, 0xffff0000, v149
	v_pk_add_f32 v[74:75], v[74:75], v[148:149]
	v_pk_add_f32 v[72:73], v[72:73], v[150:151]
	v_mul_f32_e32 v149, v75, v75
	v_mul_f32_e32 v148, v73, v73
	v_fmac_f32_e32 v148, v72, v72
	v_fmac_f32_e32 v149, v74, v74
	v_add_f32_e32 v148, v148, v149
	v_add_f32_e32 v152, v152, v148
	v_mov_b32_e32 v148, v212
	v_mov_b32_e32 v149, v213
	v_lshlrev_b32_e32 v150, 16, v148
	v_mov_b32_e32 v146, v214
	v_mov_b32_e32 v147, v215
	v_and_b32_e32 v151, 0xffff0000, v148
	v_lshlrev_b32_e32 v148, 16, v149
	v_and_b32_e32 v149, 0xffff0000, v149
	v_pk_add_f32 v[70:71], v[70:71], v[148:149]
	v_pk_add_f32 v[68:69], v[68:69], v[150:151]
	v_mul_f32_e32 v149, v71, v71
	v_mul_f32_e32 v148, v69, v69
	v_fmac_f32_e32 v148, v68, v68
	v_fmac_f32_e32 v149, v70, v70
	v_add_f32_e32 v148, v148, v149
	v_add_f32_e32 v150, v152, v148
	v_lshlrev_b32_e32 v148, 16, v146
	v_and_b32_e32 v149, 0xffff0000, v146
	v_lshlrev_b32_e32 v146, 16, v147
	v_and_b32_e32 v147, 0xffff0000, v147
	v_pk_add_f32 v[66:67], v[66:67], v[146:147]
	v_pk_add_f32 v[64:65], v[64:65], v[148:149]
	v_mul_f32_e32 v147, v67, v67
	v_mul_f32_e32 v146, v65, v65
	v_fmac_f32_e32 v146, v64, v64
	v_fmac_f32_e32 v147, v66, v66
	v_add_f32_e32 v146, v146, v147
	v_add_f32_e32 v146, v150, v146
	ds_bpermute_b32 v147, v178, v146
	v_lshl_add_u64 v[148:149], v[142:143], 2, s[0:1]
	s_waitcnt lgkmcnt(0)
	v_add_f32_e32 v146, v146, v147
	ds_bpermute_b32 v147, v179, v146
	s_and_saveexec_b64 s[0:1], vcc
	s_cbranch_execz .LBB0_991
	s_waitcnt lgkmcnt(0)
	v_add_f32_e32 v146, v146, v147
	global_atomic_add_f32 v[148:149], v146, off
.LBB0_991:
	s_or_b64 exec, exec, s[0:1]
	v_add_u32_e32 v146, 0x80, v130
	s_waitcnt lgkmcnt(0)
	v_ashrrev_i32_e32 v147, 31, v146
	v_lshlrev_b64 v[150:151], 11, v[146:147]
	v_lshl_add_u64 v[150:151], s[94:95], 0, v[150:151]
	v_lshl_add_u64 v[150:151], v[132:133], 1, v[150:151]
	s_waitcnt vmcnt(10)
	v_permlane16_swap_b32_e32 v216, v218
	v_permlane16_swap_b32_e32 v217, v219
	v_permlane16_swap_b32_e32 v224, v226
	v_permlane16_swap_b32_e32 v225, v227
	v_mov_b32_e32 v152, v216
	v_mov_b32_e32 v153, v217
	v_readlane_b32 s0, v253, 50
	v_readlane_b32 s1, v253, 51
	v_lshlrev_b32_e32 v154, 16, v152
	v_and_b32_e32 v155, 0xffff0000, v152
	v_lshlrev_b32_e32 v152, 16, v153
	v_and_b32_e32 v153, 0xffff0000, v153
	v_pk_add_f32 v[62:63], v[62:63], v[152:153]
	v_pk_add_f32 v[60:61], v[60:61], v[154:155]
	v_mul_f32_e32 v153, v63, v63
	v_mul_f32_e32 v152, v61, v61
	v_fmac_f32_e32 v152, v60, v60
	v_fmac_f32_e32 v153, v62, v62
	v_add_f32_e32 v156, v152, v153
	v_mov_b32_e32 v152, v218
	v_mov_b32_e32 v153, v219
	v_lshlrev_b32_e32 v154, 16, v152
	v_and_b32_e32 v155, 0xffff0000, v152
	v_lshlrev_b32_e32 v152, 16, v153
	v_and_b32_e32 v153, 0xffff0000, v153
	v_pk_add_f32 v[58:59], v[58:59], v[152:153]
	v_pk_add_f32 v[56:57], v[56:57], v[154:155]
	v_mul_f32_e32 v153, v59, v59
	v_mul_f32_e32 v152, v57, v57
	v_fmac_f32_e32 v152, v56, v56
	v_fmac_f32_e32 v153, v58, v58
	v_add_f32_e32 v152, v152, v153
	v_add_f32_e32 v156, v156, v152
	v_mov_b32_e32 v152, v224
	v_mov_b32_e32 v153, v225
	v_lshlrev_b32_e32 v154, 16, v152
	v_mov_b32_e32 v150, v226
	v_mov_b32_e32 v151, v227
	v_and_b32_e32 v155, 0xffff0000, v152
	v_lshlrev_b32_e32 v152, 16, v153
	v_and_b32_e32 v153, 0xffff0000, v153
	v_pk_add_f32 v[54:55], v[54:55], v[152:153]
	v_pk_add_f32 v[52:53], v[52:53], v[154:155]
	v_mul_f32_e32 v153, v55, v55
	v_mul_f32_e32 v152, v53, v53
	v_fmac_f32_e32 v152, v52, v52
	v_fmac_f32_e32 v153, v54, v54
	v_add_f32_e32 v152, v152, v153
	v_add_f32_e32 v154, v156, v152
	v_lshlrev_b32_e32 v152, 16, v150
	v_and_b32_e32 v153, 0xffff0000, v150
	v_lshlrev_b32_e32 v150, 16, v151
	v_and_b32_e32 v151, 0xffff0000, v151
	v_pk_add_f32 v[50:51], v[50:51], v[150:151]
	v_pk_add_f32 v[48:49], v[48:49], v[152:153]
	v_mul_f32_e32 v151, v51, v51
	v_mul_f32_e32 v150, v49, v49
	v_fmac_f32_e32 v150, v48, v48
	v_fmac_f32_e32 v151, v50, v50
	v_add_f32_e32 v150, v150, v151
	v_add_f32_e32 v150, v154, v150
	ds_bpermute_b32 v151, v178, v150
	v_lshl_add_u64 v[152:153], v[146:147], 2, s[0:1]
	s_waitcnt lgkmcnt(0)
	v_add_f32_e32 v150, v150, v151
	ds_bpermute_b32 v151, v179, v150
	s_and_saveexec_b64 s[0:1], vcc
	s_cbranch_execz .LBB0_993
	s_waitcnt lgkmcnt(0)
	v_add_f32_e32 v150, v150, v151
	global_atomic_add_f32 v[152:153], v150, off
; #define PG8_LAS __attribute__((address_space(3)))
;     __device__ __forceinline__ void fused(f32x4 (&acc)[2][2][4][2], const Unit& u, int wr, int wc, int fr, int fq, PG8_LAS unsigned char*, int wid, int lane) const {
;         typedef unsigned u32x2 __attribute__((ext_vector_type(2)));
;         const int col0 = u.pn * BM + wc * 32 + 4 * fq;
; #pragma unroll
;         for (int ai = 0; ai < 2; ++ai)
; #pragma unroll
;             for (int m = 0; m < 4; ++m) {
;                 const int row = u.pm * BM + ai * HALF + wr * 64 + m * 16 + fr;
;                 const size_t off = (size_t)row * 1024 + col0;
;                 float ss = 0.f;
; #pragma unroll
;                 for (int bj = 0; bj < 2; ++bj)
; #pragma unroll
;                     for (int n = 0; n < 2; ++n) { const u32x2 hb = *(const u32x2*)(baseh + off + bj * HALF + n * 16);
;                         const f32x4 o = (f32x4){__uint_as_float(hb.x << 16), __uint_as_float(hb.x & 0xffff0000u), __uint_as_float(hb.y << 16), __uint_as_float(hb.y & 0xffff0000u)} + acc[ai][bj][m][n]; acc[ai][bj][m][n] = o;
;                         ss += (o[0] * o[0] + o[1] * o[1]) + (o[2] * o[2] + o[3] * o[3]); }
;                 ss += __shfl_xor(ss, 16); ss += __shfl_xor(ss, 32);
;                 if (fq == 0) (void)__hip_atomic_fetch_add(rowss2 + row, ss, __ATOMIC_RELAXED, __HIP_MEMORY_SCOPE_AGENT);
;                 if (m & 1) asm volatile("" ::: "memory");
;             }
.LBB0_993:
	s_or_b64 exec, exec, s[0:1]
	v_add_u32_e32 v150, 0x90, v130
	s_waitcnt lgkmcnt(0)
	v_ashrrev_i32_e32 v151, 31, v150
	v_lshlrev_b64 v[154:155], 11, v[150:151]
	v_lshl_add_u64 v[154:155], s[94:95], 0, v[154:155]
	v_lshl_add_u64 v[154:155], v[132:133], 1, v[154:155]
	s_waitcnt vmcnt(9)
	v_permlane16_swap_b32_e32 v228, v230
	v_permlane16_swap_b32_e32 v229, v231
	v_permlane16_swap_b32_e32 v244, v246
	v_permlane16_swap_b32_e32 v245, v247
	v_mov_b32_e32 v156, v228
	v_mov_b32_e32 v157, v229
	v_readlane_b32 s0, v253, 50
	v_readlane_b32 s1, v253, 51
	v_lshlrev_b32_e32 v158, 16, v156
	v_and_b32_e32 v159, 0xffff0000, v156
	v_lshlrev_b32_e32 v156, 16, v157
	v_and_b32_e32 v157, 0xffff0000, v157
	v_pk_add_f32 v[46:47], v[46:47], v[156:157]
	v_pk_add_f32 v[44:45], v[44:45], v[158:159]
	v_mul_f32_e32 v157, v47, v47
	v_mul_f32_e32 v156, v45, v45
	v_fmac_f32_e32 v156, v44, v44
	v_fmac_f32_e32 v157, v46, v46
	v_add_f32_e32 v160, v156, v157
	v_mov_b32_e32 v156, v230
	v_mov_b32_e32 v157, v231
	v_lshlrev_b32_e32 v158, 16, v156
	v_and_b32_e32 v159, 0xffff0000, v156
	v_lshlrev_b32_e32 v156, 16, v157
	v_and_b32_e32 v157, 0xffff0000, v157
	v_pk_add_f32 v[42:43], v[42:43], v[156:157]
	v_pk_add_f32 v[40:41], v[40:41], v[158:159]
	v_mul_f32_e32 v157, v43, v43
	v_mul_f32_e32 v156, v41, v41
	v_fmac_f32_e32 v156, v40, v40
	v_fmac_f32_e32 v157, v42, v42
	v_add_f32_e32 v156, v156, v157
	v_add_f32_e32 v160, v160, v156
	v_mov_b32_e32 v156, v244
	v_mov_b32_e32 v157, v245
	v_lshlrev_b32_e32 v158, 16, v156
	v_mov_b32_e32 v154, v246
	v_mov_b32_e32 v155, v247
	v_and_b32_e32 v159, 0xffff0000, v156
	v_lshlrev_b32_e32 v156, 16, v157
	v_and_b32_e32 v157, 0xffff0000, v157
	v_pk_add_f32 v[38:39], v[38:39], v[156:157]
	v_pk_add_f32 v[36:37], v[36:37], v[158:159]
	v_mul_f32_e32 v157, v39, v39
	v_mul_f32_e32 v156, v37, v37
	v_fmac_f32_e32 v156, v36, v36
	v_fmac_f32_e32 v157, v38, v38
	v_add_f32_e32 v156, v156, v157
	v_add_f32_e32 v158, v160, v156
	v_lshlrev_b32_e32 v156, 16, v154
	v_and_b32_e32 v157, 0xffff0000, v154
	v_lshlrev_b32_e32 v154, 16, v155
	v_and_b32_e32 v155, 0xffff0000, v155
	v_pk_add_f32 v[34:35], v[34:35], v[154:155]
	v_pk_add_f32 v[32:33], v[32:33], v[156:157]
	v_mul_f32_e32 v155, v35, v35
	v_mul_f32_e32 v154, v33, v33
	v_fmac_f32_e32 v154, v32, v32
	v_fmac_f32_e32 v155, v34, v34
	v_add_f32_e32 v154, v154, v155
	v_add_f32_e32 v154, v158, v154
	ds_bpermute_b32 v155, v178, v154
	v_lshl_add_u64 v[156:157], v[150:151], 2, s[0:1]
	s_waitcnt lgkmcnt(0)
	v_add_f32_e32 v154, v154, v155
	ds_bpermute_b32 v155, v179, v154
	s_and_saveexec_b64 s[0:1], vcc
	s_cbranch_execz .LBB0_995
	s_waitcnt lgkmcnt(0)
	v_add_f32_e32 v154, v154, v155
	global_atomic_add_f32 v[156:157], v154, off
; #define PG8_LAS __attribute__((address_space(3)))
;     __device__ __forceinline__ void fused(f32x4 (&acc)[2][2][4][2], const Unit& u, int wr, int wc, int fr, int fq, PG8_LAS unsigned char*, int wid, int lane) const {
;         typedef unsigned u32x2 __attribute__((ext_vector_type(2)));
;         const int col0 = u.pn * BM + wc * 32 + 4 * fq;
; #pragma unroll
;         for (int ai = 0; ai < 2; ++ai)
; #pragma unroll
;             for (int m = 0; m < 4; ++m) {
;                 const int row = u.pm * BM + ai * HALF + wr * 64 + m * 16 + fr;
;                 const size_t off = (size_t)row * 1024 + col0;
;                 float ss = 0.f;
; #pragma unroll
;                 for (int bj = 0; bj < 2; ++bj)
; #pragma unroll
;                     for (int n = 0; n < 2; ++n) { const u32x2 hb = *(const u32x2*)(baseh + off + bj * HALF + n * 16);
;                         const f32x4 o = (f32x4){__uint_as_float(hb.x << 16), __uint_as_float(hb.x & 0xffff0000u), __uint_as_float(hb.y << 16), __uint_as_float(hb.y & 0xffff0000u)} + acc[ai][bj][m][n]; acc[ai][bj][m][n] = o;
;                         ss += (o[0] * o[0] + o[1] * o[1]) + (o[2] * o[2] + o[3] * o[3]); }
;                 ss += __shfl_xor(ss, 16); ss += __shfl_xor(ss, 32);
;                 if (fq == 0) (void)__hip_atomic_fetch_add(rowss2 + row, ss, __ATOMIC_RELAXED, __HIP_MEMORY_SCOPE_AGENT);
;                 if (m & 1) asm volatile("" ::: "memory");
;             }
.LBB0_995:
	s_or_b64 exec, exec, s[0:1]
	v_add_u32_e32 v154, 0xa0, v130
	s_waitcnt lgkmcnt(0)
	v_ashrrev_i32_e32 v155, 31, v154
	v_lshlrev_b64 v[158:159], 11, v[154:155]
	v_lshl_add_u64 v[158:159], s[94:95], 0, v[158:159]
	v_lshl_add_u64 v[158:159], v[132:133], 1, v[158:159]
	s_waitcnt vmcnt(7)
	v_permlane16_swap_b32_e32 v248, v250
	v_permlane16_swap_b32_e32 v249, v251
	v_permlane16_swap_b32_e32 v184, v186
	v_permlane16_swap_b32_e32 v185, v187
	v_mov_b32_e32 v160, v248
	v_mov_b32_e32 v161, v249
	v_readlane_b32 s0, v253, 50
	v_readlane_b32 s1, v253, 51
	v_lshlrev_b32_e32 v162, 16, v160
	v_and_b32_e32 v163, 0xffff0000, v160
	v_lshlrev_b32_e32 v160, 16, v161
	v_and_b32_e32 v161, 0xffff0000, v161
	v_pk_add_f32 v[30:31], v[30:31], v[160:161]
	v_pk_add_f32 v[28:29], v[28:29], v[162:163]
	v_mul_f32_e32 v161, v31, v31
	v_mul_f32_e32 v160, v29, v29
	v_fmac_f32_e32 v160, v28, v28
	v_fmac_f32_e32 v161, v30, v30
	v_add_f32_e32 v164, v160, v161
	v_mov_b32_e32 v160, v250
	v_mov_b32_e32 v161, v251
	v_lshlrev_b32_e32 v162, 16, v160
	v_and_b32_e32 v163, 0xffff0000, v160
	v_lshlrev_b32_e32 v160, 16, v161
	v_and_b32_e32 v161, 0xffff0000, v161
	v_pk_add_f32 v[26:27], v[26:27], v[160:161]
	v_pk_add_f32 v[24:25], v[24:25], v[162:163]
	v_mul_f32_e32 v161, v27, v27
	v_mul_f32_e32 v160, v25, v25
	v_fmac_f32_e32 v160, v24, v24
	v_fmac_f32_e32 v161, v26, v26
	v_add_f32_e32 v160, v160, v161
	v_add_f32_e32 v164, v164, v160
	v_mov_b32_e32 v160, v184
	v_mov_b32_e32 v161, v185
	v_lshlrev_b32_e32 v162, 16, v160
	v_mov_b32_e32 v158, v186
	v_mov_b32_e32 v159, v187
	v_and_b32_e32 v163, 0xffff0000, v160
	v_lshlrev_b32_e32 v160, 16, v161
	v_and_b32_e32 v161, 0xffff0000, v161
	v_pk_add_f32 v[22:23], v[22:23], v[160:161]
	v_pk_add_f32 v[20:21], v[20:21], v[162:163]
	v_mul_f32_e32 v161, v23, v23
	v_mul_f32_e32 v160, v21, v21
	v_fmac_f32_e32 v160, v20, v20
	v_fmac_f32_e32 v161, v22, v22
	v_add_f32_e32 v160, v160, v161
	v_add_f32_e32 v162, v164, v160
	v_lshl_add_u64 v[164:165], v[154:155], 2, s[0:1]
	v_lshlrev_b32_e32 v160, 16, v158
	v_and_b32_e32 v161, 0xffff0000, v158
	v_lshlrev_b32_e32 v158, 16, v159
	v_and_b32_e32 v159, 0xffff0000, v159
	v_pk_add_f32 v[18:19], v[18:19], v[158:159]
	v_pk_add_f32 v[16:17], v[16:17], v[160:161]
	v_mul_f32_e32 v159, v19, v19
	v_mul_f32_e32 v158, v17, v17
	v_fmac_f32_e32 v158, v16, v16
	v_fmac_f32_e32 v159, v18, v18
	v_add_f32_e32 v158, v158, v159
	v_add_f32_e32 v158, v162, v158
	ds_bpermute_b32 v159, v178, v158
	s_waitcnt lgkmcnt(0)
	v_add_f32_e32 v158, v158, v159
	ds_bpermute_b32 v159, v179, v158
	s_and_saveexec_b64 s[0:1], vcc
	s_cbranch_execz .LBB0_997
	s_waitcnt lgkmcnt(0)
	v_add_f32_e32 v158, v158, v159
	global_atomic_add_f32 v[164:165], v158, off
.LBB0_997:
	s_or_b64 exec, exec, s[0:1]
	v_add_u32_e32 v158, 0xb0, v130
	s_waitcnt lgkmcnt(0)
	v_ashrrev_i32_e32 v159, 31, v158
	v_lshlrev_b64 v[160:161], 11, v[158:159]
	v_lshl_add_u64 v[160:161], s[94:95], 0, v[160:161]
	v_lshl_add_u64 v[174:175], v[132:133], 1, v[160:161]
	s_waitcnt vmcnt(6)
	v_permlane16_swap_b32_e32 v188, v190
	v_permlane16_swap_b32_e32 v189, v191
	v_permlane16_swap_b32_e32 v192, v194
	v_permlane16_swap_b32_e32 v193, v195
	v_mov_b32_e32 v160, v188
	v_mov_b32_e32 v161, v189
	v_readlane_b32 s0, v253, 50
	v_readlane_b32 s1, v253, 51
	v_lshlrev_b32_e32 v162, 16, v160
	v_and_b32_e32 v163, 0xffff0000, v160
	v_lshlrev_b32_e32 v160, 16, v161
	v_and_b32_e32 v161, 0xffff0000, v161
	v_pk_add_f32 v[160:161], v[14:15], v[160:161]
	v_pk_add_f32 v[162:163], v[12:13], v[162:163]
	v_mul_f32_e32 v13, v161, v161
	v_mul_f32_e32 v12, v163, v163
	v_fmac_f32_e32 v12, v162, v162
	v_fmac_f32_e32 v13, v160, v160
	v_add_f32_e32 v170, v12, v13
	v_mov_b32_e32 v12, v190
	v_mov_b32_e32 v13, v191
	v_lshlrev_b32_e32 v14, 16, v12
	v_and_b32_e32 v15, 0xffff0000, v12
	v_lshlrev_b32_e32 v12, 16, v13
	v_and_b32_e32 v13, 0xffff0000, v13
	v_pk_add_f32 v[166:167], v[10:11], v[12:13]
	v_pk_add_f32 v[168:169], v[8:9], v[14:15]
	v_mul_f32_e32 v9, v167, v167
	v_mul_f32_e32 v8, v169, v169
	v_fmac_f32_e32 v8, v168, v168
	v_fmac_f32_e32 v9, v166, v166
	v_add_f32_e32 v8, v8, v9
	v_add_f32_e32 v12, v170, v8
	v_mov_b32_e32 v8, v192
	v_mov_b32_e32 v9, v193
	v_lshlrev_b32_e32 v10, 16, v8
	v_and_b32_e32 v11, 0xffff0000, v8
	v_lshlrev_b32_e32 v8, 16, v9
	v_and_b32_e32 v9, 0xffff0000, v9
	v_pk_add_f32 v[170:171], v[6:7], v[8:9]
	v_pk_add_f32 v[172:173], v[4:5], v[10:11]
	v_mul_f32_e32 v5, v171, v171
	v_mul_f32_e32 v4, v173, v173
	v_fmac_f32_e32 v4, v172, v172
	v_fmac_f32_e32 v5, v170, v170
	v_add_f32_e32 v4, v4, v5
	v_add_f32_e32 v8, v12, v4
	v_mov_b32_e32 v4, v194
	v_mov_b32_e32 v5, v195
	v_lshlrev_b32_e32 v6, 16, v4
	v_and_b32_e32 v7, 0xffff0000, v4
	v_lshlrev_b32_e32 v4, 16, v5
	v_and_b32_e32 v5, 0xffff0000, v5
	v_pk_add_f32 v[174:175], v[2:3], v[4:5]
	v_pk_add_f32 v[176:177], v[0:1], v[6:7]
	v_mul_f32_e32 v1, v175, v175
	v_mul_f32_e32 v0, v177, v177
	v_fmac_f32_e32 v0, v176, v176
	v_fmac_f32_e32 v1, v174, v174
	v_add_f32_e32 v0, v0, v1
	v_add_f32_e32 v0, v8, v0
	ds_bpermute_b32 v1, v178, v0
	s_waitcnt lgkmcnt(0)
	v_add_f32_e32 v0, v0, v1
	ds_bpermute_b32 v1, v179, v0
	v_lshl_add_u64 v[178:179], v[158:159], 2, s[0:1]
	s_and_saveexec_b64 s[0:1], vcc
	s_cbranch_execz .LBB0_999
	s_waitcnt lgkmcnt(0)
	v_add_f32_e32 v0, v0, v1
	global_atomic_add_f32 v[178:179], v0, off

;     __device__ __forceinline__ void fused(f32x4 (&acc)[2][2][4][2], const Unit& u, int wr, int wc, int fr, int fq, PG8_LAS unsigned char*, int wid, int lane) const {
;     ...
;         f32x4 wv[2][2];
; #pragma unroll
;         for (int bj = 0; bj < 2; ++bj)
; #pragma unroll
;             for (int n = 0; n < 2; ++n) wv[bj][n] = *(const f32x4*)(fw + col0 + bj * HALF + n * 16);
; #pragma unroll
;         for (int ai = 0; ai < 2; ++ai)
; #pragma unroll
;             for (int m = 0; m < 4; ++m) {
;                 const int row = u.pm * BM + ai * HALF + wr * 64 + m * 16 + fr;
;                 const size_t off = (size_t)row * 1024 + col0;
;                 const float rs = __builtin_amdgcn_rsqf(__hip_atomic_load(rowss2 + row, __ATOMIC_RELAXED, __HIP_MEMORY_SCOPE_AGENT) * (1.0f / 1024.0f) + 1e-6f);
; #pragma unroll
;                 for (int bj = 0; bj < 2; ++bj)
; #pragma unroll
;                     for (int n = 0; n < 2; ++n) *(f32x4*)(out + off + bj * HALF + n * 16) = acc[ai][bj][m][n] * rs * wv[bj][n];
;             }
.LBB0_1008:
	v_lshlrev_b64 v[132:133], 2, v[132:133]
	s_barrier
	s_waitcnt lgkmcnt(0)
	v_lshl_add_u64 v[0:1], v[128:129], 0, v[132:133]
	global_load_dwordx4 v[12:15], v[0:1], off
	global_load_dwordx4 v[8:11], v[0:1], off offset:64
	global_load_dwordx4 v[4:7], v[0:1], off offset:512
	s_nop 0
	global_load_dwordx4 v[0:3], v[0:1], off offset:576
	global_load_dword v222, v[136:137], off sc1
	global_load_dword v223, v[140:141], off sc1
	global_load_dword v232, v[144:145], off sc1
	global_load_dword v233, v[148:149], off sc1
	global_load_dword v238, v[152:153], off sc1
	global_load_dword v239, v[156:157], off sc1
	global_load_dword v240, v[164:165], off sc1
	global_load_dword v242, v[178:179], off sc1
	s_nop 0
	s_waitcnt vmcnt(7)
	v_mov_b32_e32 v128, v222
	v_readlane_b32 s0, v252, 3
	v_lshlrev_b64 v[130:131], 12, v[130:131]
	v_readlane_b32 s1, v252, 4
	v_fmamk_f32 v128, v128, 0x3a800000, v235
	v_rsq_f32_e32 v128, v128
	v_lshl_add_u64 v[130:131], s[0:1], 0, v[130:131]
	v_lshl_add_u64 v[130:131], v[130:131], 0, v[132:133]
	v_pk_mul_f32 v[124:125], v[124:125], v[128:129] op_sel_hi:[1,0]
	v_pk_mul_f32 v[126:127], v[126:127], v[128:129] op_sel_hi:[1,0]
	v_pk_mul_f32 v[120:121], v[120:121], v[128:129] op_sel_hi:[1,0]
	v_pk_mul_f32 v[122:123], v[122:123], v[128:129] op_sel_hi:[1,0]
	v_pk_mul_f32 v[136:137], v[116:117], v[128:129] op_sel_hi:[1,0]
	v_pk_mul_f32 v[180:181], v[118:119], v[128:129] op_sel_hi:[1,0]
	v_pk_mul_f32 v[182:183], v[112:113], v[128:129] op_sel_hi:[1,0]
	v_pk_mul_f32 v[128:129], v[114:115], v[128:129] op_sel_hi:[1,0]
	s_waitcnt lgkmcnt(0)
	v_pk_mul_f32 v[114:115], v[14:15], v[126:127]
	v_pk_mul_f32 v[112:113], v[12:13], v[124:125]
	v_pk_mul_f32 v[118:119], v[10:11], v[122:123]
	v_pk_mul_f32 v[116:117], v[8:9], v[120:121]
	v_pk_mul_f32 v[122:123], v[6:7], v[180:181]
	v_pk_mul_f32 v[120:121], v[4:5], v[136:137]
	v_pk_mul_f32 v[126:127], v[2:3], v[128:129]
	v_pk_mul_f32 v[124:125], v[0:1], v[182:183]
	global_store_dwordx4 v[130:131], v[112:115], off
	global_store_dwordx4 v[130:131], v[116:119], off offset:64
	global_store_dwordx4 v[130:131], v[120:123], off offset:512
	global_store_dwordx4 v[130:131], v[124:127], off offset:576
	s_waitcnt vmcnt(10)
	v_mov_b32_e32 v112, v223
	v_lshlrev_b64 v[114:115], 12, v[134:135]
	v_lshl_add_u64 v[114:115], s[0:1], 0, v[114:115]
	v_lshl_add_u64 v[114:115], v[114:115], 0, v[132:133]
	v_fmamk_f32 v112, v112, 0x3a800000, v235
	v_rsq_f32_e32 v112, v112
	s_nop 0
	v_pk_mul_f32 v[108:109], v[108:109], v[112:113] op_sel_hi:[1,0]
	v_pk_mul_f32 v[110:111], v[110:111], v[112:113] op_sel_hi:[1,0]
	v_pk_mul_f32 v[104:105], v[104:105], v[112:113] op_sel_hi:[1,0]
	v_pk_mul_f32 v[106:107], v[106:107], v[112:113] op_sel_hi:[1,0]
	v_pk_mul_f32 v[116:117], v[100:101], v[112:113] op_sel_hi:[1,0]
	v_pk_mul_f32 v[118:119], v[102:103], v[112:113] op_sel_hi:[1,0]
	v_pk_mul_f32 v[120:121], v[96:97], v[112:113] op_sel_hi:[1,0]
	v_pk_mul_f32 v[112:113], v[98:99], v[112:113] op_sel_hi:[1,0]
	v_pk_mul_f32 v[98:99], v[14:15], v[110:111]
	v_pk_mul_f32 v[96:97], v[12:13], v[108:109]
	v_pk_mul_f32 v[102:103], v[10:11], v[106:107]
	v_pk_mul_f32 v[100:101], v[8:9], v[104:105]
	v_pk_mul_f32 v[106:107], v[6:7], v[118:119]
	v_pk_mul_f32 v[104:105], v[4:5], v[116:117]
	v_pk_mul_f32 v[110:111], v[2:3], v[112:113]
	v_pk_mul_f32 v[108:109], v[0:1], v[120:121]
	global_store_dwordx4 v[114:115], v[96:99], off
	global_store_dwordx4 v[114:115], v[100:103], off offset:64
	global_store_dwordx4 v[114:115], v[104:107], off offset:512
	global_store_dwordx4 v[114:115], v[108:111], off offset:576
	s_waitcnt vmcnt(13)
	v_mov_b32_e32 v96, v232
	v_lshlrev_b64 v[98:99], 12, v[138:139]
	v_lshl_add_u64 v[98:99], s[0:1], 0, v[98:99]
	v_lshl_add_u64 v[98:99], v[98:99], 0, v[132:133]
	v_fmamk_f32 v96, v96, 0x3a800000, v235
	v_rsq_f32_e32 v96, v96
	s_nop 0
	v_pk_mul_f32 v[92:93], v[92:93], v[96:97] op_sel_hi:[1,0]
	v_pk_mul_f32 v[94:95], v[94:95], v[96:97] op_sel_hi:[1,0]
	v_pk_mul_f32 v[88:89], v[88:89], v[96:97] op_sel_hi:[1,0]
	v_pk_mul_f32 v[90:91], v[90:91], v[96:97] op_sel_hi:[1,0]
	v_pk_mul_f32 v[100:101], v[84:85], v[96:97] op_sel_hi:[1,0]
	v_pk_mul_f32 v[102:103], v[86:87], v[96:97] op_sel_hi:[1,0]
	v_pk_mul_f32 v[104:105], v[80:81], v[96:97] op_sel_hi:[1,0]
	v_pk_mul_f32 v[96:97], v[82:83], v[96:97] op_sel_hi:[1,0]
	v_pk_mul_f32 v[82:83], v[14:15], v[94:95]
	v_pk_mul_f32 v[80:81], v[12:13], v[92:93]
	v_pk_mul_f32 v[86:87], v[10:11], v[90:91]
	v_pk_mul_f32 v[84:85], v[8:9], v[88:89]
	v_pk_mul_f32 v[90:91], v[6:7], v[102:103]
	v_pk_mul_f32 v[88:89], v[4:5], v[100:101]
	v_pk_mul_f32 v[94:95], v[2:3], v[96:97]
	v_pk_mul_f32 v[92:93], v[0:1], v[104:105]
	global_store_dwordx4 v[98:99], v[80:83], off
	global_store_dwordx4 v[98:99], v[84:87], off offset:64
	global_store_dwordx4 v[98:99], v[88:91], off offset:512
	global_store_dwordx4 v[98:99], v[92:95], off offset:576
	s_waitcnt vmcnt(16)
	v_mov_b32_e32 v80, v233
	v_lshlrev_b64 v[82:83], 12, v[142:143]
	v_lshl_add_u64 v[82:83], s[0:1], 0, v[82:83]
	v_lshl_add_u64 v[82:83], v[82:83], 0, v[132:133]
	v_fmamk_f32 v80, v80, 0x3a800000, v235
	v_rsq_f32_e32 v80, v80
	s_nop 0
	v_pk_mul_f32 v[76:77], v[76:77], v[80:81] op_sel_hi:[1,0]
	v_pk_mul_f32 v[78:79], v[78:79], v[80:81] op_sel_hi:[1,0]
	v_pk_mul_f32 v[72:73], v[72:73], v[80:81] op_sel_hi:[1,0]
	v_pk_mul_f32 v[74:75], v[74:75], v[80:81] op_sel_hi:[1,0]
	v_pk_mul_f32 v[84:85], v[68:69], v[80:81] op_sel_hi:[1,0]
	v_pk_mul_f32 v[86:87], v[70:71], v[80:81] op_sel_hi:[1,0]
	v_pk_mul_f32 v[88:89], v[64:65], v[80:81] op_sel_hi:[1,0]
	v_pk_mul_f32 v[80:81], v[66:67], v[80:81] op_sel_hi:[1,0]
	v_pk_mul_f32 v[66:67], v[14:15], v[78:79]
	v_pk_mul_f32 v[64:65], v[12:13], v[76:77]
	v_pk_mul_f32 v[70:71], v[10:11], v[74:75]
	v_pk_mul_f32 v[68:69], v[8:9], v[72:73]
	v_pk_mul_f32 v[74:75], v[6:7], v[86:87]
	v_pk_mul_f32 v[72:73], v[4:5], v[84:85]
	v_pk_mul_f32 v[78:79], v[2:3], v[80:81]
	v_pk_mul_f32 v[76:77], v[0:1], v[88:89]
	global_store_dwordx4 v[82:83], v[64:67], off
	global_store_dwordx4 v[82:83], v[68:71], off offset:64
	global_store_dwordx4 v[82:83], v[72:75], off offset:512
	global_store_dwordx4 v[82:83], v[76:79], off offset:576
	s_waitcnt vmcnt(19)
;     __device__ __forceinline__ void fused(f32x4 (&acc)[2][2][4][2], const Unit& u, int wr, int wc, int fr, int fq, PG8_LAS unsigned char*, int wid, int lane) const {
;     ...
;         f32x4 wv[2][2];
; #pragma unroll
;         for (int bj = 0; bj < 2; ++bj)
; #pragma unroll
;             for (int n = 0; n < 2; ++n) wv[bj][n] = *(const f32x4*)(fw + col0 + bj * HALF + n * 16);
; #pragma unroll
;         for (int ai = 0; ai < 2; ++ai)
; #pragma unroll
;             for (int m = 0; m < 4; ++m) {
;                 const int row = u.pm * BM + ai * HALF + wr * 64 + m * 16 + fr;
;                 const size_t off = (size_t)row * 1024 + col0;
;                 const float rs = __builtin_amdgcn_rsqf(__hip_atomic_load(rowss2 + row, __ATOMIC_RELAXED, __HIP_MEMORY_SCOPE_AGENT) * (1.0f / 1024.0f) + 1e-6f);
; #pragma unroll
;                 for (int bj = 0; bj < 2; ++bj)
; #pragma unroll
;                     for (int n = 0; n < 2; ++n) *(f32x4*)(out + off + bj * HALF + n * 16) = acc[ai][bj][m][n] * rs * wv[bj][n];
;             }
	v_mov_b32_e32 v64, v238
	v_lshlrev_b64 v[66:67], 12, v[146:147]
	v_lshl_add_u64 v[66:67], s[0:1], 0, v[66:67]
	v_lshl_add_u64 v[66:67], v[66:67], 0, v[132:133]
	v_fmamk_f32 v64, v64, 0x3a800000, v235
	v_rsq_f32_e32 v64, v64
	s_nop 0
	v_pk_mul_f32 v[60:61], v[60:61], v[64:65] op_sel_hi:[1,0]
	v_pk_mul_f32 v[62:63], v[62:63], v[64:65] op_sel_hi:[1,0]
	v_pk_mul_f32 v[56:57], v[56:57], v[64:65] op_sel_hi:[1,0]
	v_pk_mul_f32 v[58:59], v[58:59], v[64:65] op_sel_hi:[1,0]
	v_pk_mul_f32 v[68:69], v[52:53], v[64:65] op_sel_hi:[1,0]
	v_pk_mul_f32 v[70:71], v[54:55], v[64:65] op_sel_hi:[1,0]
	v_pk_mul_f32 v[72:73], v[48:49], v[64:65] op_sel_hi:[1,0]
	v_pk_mul_f32 v[64:65], v[50:51], v[64:65] op_sel_hi:[1,0]
	v_pk_mul_f32 v[50:51], v[14:15], v[62:63]
	v_pk_mul_f32 v[48:49], v[12:13], v[60:61]
	v_pk_mul_f32 v[54:55], v[10:11], v[58:59]
	v_pk_mul_f32 v[52:53], v[8:9], v[56:57]
	v_pk_mul_f32 v[58:59], v[6:7], v[70:71]
	v_pk_mul_f32 v[56:57], v[4:5], v[68:69]
	v_pk_mul_f32 v[62:63], v[2:3], v[64:65]
	v_pk_mul_f32 v[60:61], v[0:1], v[72:73]
	global_store_dwordx4 v[66:67], v[48:51], off
	global_store_dwordx4 v[66:67], v[52:55], off offset:64
	global_store_dwordx4 v[66:67], v[56:59], off offset:512
	global_store_dwordx4 v[66:67], v[60:63], off offset:576
	s_waitcnt vmcnt(22)
	v_mov_b32_e32 v48, v239
	v_lshlrev_b64 v[50:51], 12, v[150:151]
	v_lshl_add_u64 v[50:51], s[0:1], 0, v[50:51]
	v_lshl_add_u64 v[50:51], v[50:51], 0, v[132:133]
	v_fmamk_f32 v48, v48, 0x3a800000, v235
	v_rsq_f32_e32 v48, v48
	s_nop 0
	v_pk_mul_f32 v[44:45], v[44:45], v[48:49] op_sel_hi:[1,0]
	v_pk_mul_f32 v[46:47], v[46:47], v[48:49] op_sel_hi:[1,0]
	v_pk_mul_f32 v[40:41], v[40:41], v[48:49] op_sel_hi:[1,0]
	v_pk_mul_f32 v[42:43], v[42:43], v[48:49] op_sel_hi:[1,0]
	v_pk_mul_f32 v[52:53], v[36:37], v[48:49] op_sel_hi:[1,0]
	v_pk_mul_f32 v[54:55], v[38:39], v[48:49] op_sel_hi:[1,0]
	v_pk_mul_f32 v[56:57], v[32:33], v[48:49] op_sel_hi:[1,0]
	v_pk_mul_f32 v[48:49], v[34:35], v[48:49] op_sel_hi:[1,0]
	v_pk_mul_f32 v[34:35], v[14:15], v[46:47]
	v_pk_mul_f32 v[32:33], v[12:13], v[44:45]
	v_pk_mul_f32 v[38:39], v[10:11], v[42:43]
	v_pk_mul_f32 v[36:37], v[8:9], v[40:41]
	v_pk_mul_f32 v[42:43], v[6:7], v[54:55]
	v_pk_mul_f32 v[40:41], v[4:5], v[52:53]
	v_pk_mul_f32 v[46:47], v[2:3], v[48:49]
	v_pk_mul_f32 v[44:45], v[0:1], v[56:57]
	global_store_dwordx4 v[50:51], v[32:35], off
	global_store_dwordx4 v[50:51], v[36:39], off offset:64
	global_store_dwordx4 v[50:51], v[40:43], off offset:512
	global_store_dwordx4 v[50:51], v[44:47], off offset:576
	s_waitcnt vmcnt(25)
	v_mov_b32_e32 v32, v240
	v_lshlrev_b64 v[34:35], 12, v[154:155]
	v_lshl_add_u64 v[34:35], s[0:1], 0, v[34:35]
	v_lshl_add_u64 v[34:35], v[34:35], 0, v[132:133]
	v_fmamk_f32 v32, v32, 0x3a800000, v235
	v_rsq_f32_e32 v32, v32
	s_nop 0
	v_pk_mul_f32 v[28:29], v[28:29], v[32:33] op_sel_hi:[1,0]
	v_pk_mul_f32 v[30:31], v[30:31], v[32:33] op_sel_hi:[1,0]
	v_pk_mul_f32 v[24:25], v[24:25], v[32:33] op_sel_hi:[1,0]
	v_pk_mul_f32 v[26:27], v[26:27], v[32:33] op_sel_hi:[1,0]
	v_pk_mul_f32 v[36:37], v[20:21], v[32:33] op_sel_hi:[1,0]
	v_pk_mul_f32 v[38:39], v[22:23], v[32:33] op_sel_hi:[1,0]
	v_pk_mul_f32 v[40:41], v[16:17], v[32:33] op_sel_hi:[1,0]
	v_pk_mul_f32 v[32:33], v[18:19], v[32:33] op_sel_hi:[1,0]
	v_pk_mul_f32 v[18:19], v[14:15], v[30:31]
	v_pk_mul_f32 v[16:17], v[12:13], v[28:29]
	v_pk_mul_f32 v[22:23], v[10:11], v[26:27]
	v_pk_mul_f32 v[20:21], v[8:9], v[24:25]
	v_pk_mul_f32 v[26:27], v[6:7], v[38:39]
	v_pk_mul_f32 v[24:25], v[4:5], v[36:37]
	v_pk_mul_f32 v[30:31], v[2:3], v[32:33]
	v_pk_mul_f32 v[28:29], v[0:1], v[40:41]
	global_store_dwordx4 v[34:35], v[16:19], off
	global_store_dwordx4 v[34:35], v[20:23], off offset:64
	global_store_dwordx4 v[34:35], v[24:27], off offset:512
	global_store_dwordx4 v[34:35], v[28:31], off offset:576
	s_waitcnt vmcnt(28)
	v_mov_b32_e32 v16, v242
	v_lshlrev_b64 v[18:19], 12, v[158:159]
	v_lshl_add_u64 v[18:19], s[0:1], 0, v[18:19]
	v_lshl_add_u64 v[18:19], v[18:19], 0, v[132:133]
	v_fmamk_f32 v16, v16, 0x3a800000, v235
	v_rsq_f32_e32 v16, v16
	s_nop 0
	v_pk_mul_f32 v[20:21], v[162:163], v[16:17] op_sel_hi:[1,0]
	v_pk_mul_f32 v[22:23], v[160:161], v[16:17] op_sel_hi:[1,0]
	v_pk_mul_f32 v[24:25], v[168:169], v[16:17] op_sel_hi:[1,0]
	v_pk_mul_f32 v[26:27], v[166:167], v[16:17] op_sel_hi:[1,0]
	v_pk_mul_f32 v[28:29], v[172:173], v[16:17] op_sel_hi:[1,0]
	v_pk_mul_f32 v[30:31], v[170:171], v[16:17] op_sel_hi:[1,0]
	v_pk_mul_f32 v[32:33], v[176:177], v[16:17] op_sel_hi:[1,0]
	v_pk_mul_f32 v[16:17], v[174:175], v[16:17] op_sel_hi:[1,0]
	v_pk_mul_f32 v[14:15], v[14:15], v[22:23]
	v_pk_mul_f32 v[12:13], v[12:13], v[20:21]
	v_pk_mul_f32 v[10:11], v[10:11], v[26:27]
	v_pk_mul_f32 v[8:9], v[8:9], v[24:25]
	v_pk_mul_f32 v[6:7], v[6:7], v[30:31]
	v_pk_mul_f32 v[4:5], v[4:5], v[28:29]
	v_pk_mul_f32 v[2:3], v[2:3], v[16:17]
	v_pk_mul_f32 v[0:1], v[0:1], v[32:33]
	global_store_dwordx4 v[18:19], v[12:15], off
	global_store_dwordx4 v[18:19], v[8:11], off offset:64
	global_store_dwordx4 v[18:19], v[4:7], off offset:512
	global_store_dwordx4 v[18:19], v[0:3], off offset:576
